# mixer B epilogue: second query tile's gate rows and the head-norm weight vectors loaded together with the first tile's gate rows; weights loaded once
# baseline (speedup 1.0000x reference)
; #define LAS __attribute__((address_space(3)))
; DI void mixerB2_unit(int u, int l, const bf16* PROJ, bf16* YC, const float* dlam_l, const float* dnw_l, const float* kmax_l, LAS char* lds, int tid, int wave, int lane) {
;     ...
;     float pa = 0.f, pb = 0.f;
;     if (lane < 32) { pa = dlam_l[lane] * dlam_l[32 + lane]; pb = dlam_l[64 + lane] * dlam_l[96 + lane]; }
;     pa = wave_sum(pa); pb = wave_sum(pb);
;     const float lam_init = 0.8f - 0.6f * __expf(-0.3f * (float)l);
;     const float lam = __expf(pa) - __expf(pb) + lam_init;
;     LAS char* sc = lds + 4 * KV_TILE + wave * (16 * VT_PITCH);
; #pragma unroll
;     for (int qt = 0; qt < 2; ++qt) {
;         const int tok0 = q0w + 16 * qt;
;         const float i1 = 1.f / ol1[qt][0], i2 = lam / ol2[qt][0];
;         f32x4 o[4]; float ss = 0.f;
; #pragma unroll
;         for (int c = 0; c < 4; ++c) { o[c] = o1[qt][c] * i1 - o2[qt][c] * i2; ss += (o[c][0] * o[c][0] + o[c][1] * o[c][1]) + (o[c][2] * o[c][2] + o[c][3] * o[c][3]); }
;         ss += __shfl_xor(ss, 16); ss += __shfl_xor(ss, 32);
;         const float rstd = rsqrtf(ss * (1.f / 64.f) + EPS) * (1.f - lam_init);
;         rows16_load(sc, gbase, 64, tok0, 1, lane);
;         u32x2 gv[4];
; #pragma unroll
;         for (int c = 0; c < 4; ++c) gv[c] = *(const LAS u32x2*)(sc + r * VT_PITCH + (16 * c + 4 * g) * 2);
; #pragma unroll
;         for (int c = 0; c < 4; ++c) { const int dd = 16 * c + 4 * g;
;             const f32x4 nw = *(const f32x4*)(dnw_l + dd);
.LBB0_251:
	s_or_b64 exec, exec, s[0:1]
	ds_bpermute_b32 v6, v201, v4
	ds_bpermute_b32 v7, v201, v5
	s_or_b32 s0, s43, 16
	s_add_u32 s26, s42, s26
	v_or_b32_e32 v90, s43, v207
	s_waitcnt lgkmcnt(1)
	v_add_f32_e32 v4, v4, v6
	s_waitcnt lgkmcnt(0)
	v_add_f32_e32 v5, v5, v7
	ds_bpermute_b32 v6, v202, v4
	ds_bpermute_b32 v7, v202, v5
	v_or_b32_e32 v54, s43, v208
	s_addc_u32 s27, s34, s27
	v_ashrrev_i32_e32 v91, 31, v90
	s_waitcnt lgkmcnt(1)
	v_add_f32_e32 v4, v4, v6
	s_waitcnt lgkmcnt(0)
	v_add_f32_e32 v5, v5, v7
	ds_bpermute_b32 v6, v203, v4
	ds_bpermute_b32 v7, v203, v5
	v_ashrrev_i32_e32 v55, 31, v54
	s_lshl_b64 s[20:21], s[20:21], 22
	s_add_u32 s1, s8, s20
	s_waitcnt lgkmcnt(1)
	v_add_f32_e32 v4, v4, v6
	s_waitcnt lgkmcnt(0)
	v_add_f32_e32 v5, v5, v7
	ds_bpermute_b32 v6, v204, v4
	ds_bpermute_b32 v7, v204, v5
	s_waitcnt vmcnt(0) lgkmcnt(1)
	v_add_f32_e32 v8, v4, v6
	s_waitcnt lgkmcnt(0)
	v_add_f32_e32 v9, v5, v7
	ds_bpermute_b32 v10, v184, v8
	ds_bpermute_b32 v11, v184, v9
	v_lshlrev_b64 v[4:5], 7, v[90:91]
	v_lshlrev_b64 v[6:7], 7, v[54:55]
	s_waitcnt lgkmcnt(1)
	v_add_f32_e32 v10, v8, v10
	s_waitcnt lgkmcnt(0)
	v_add_f32_e32 v11, v9, v11
	ds_bpermute_b32 v49, v185, v10
	ds_bpermute_b32 v50, v185, v11
	v_lshl_add_u64 v[8:9], s[26:27], 0, v[188:189]
	s_mov_b64 s[26:27], 0x3800000
	v_lshl_add_u64 v[86:87], v[8:9], 0, s[26:27]
	s_waitcnt lgkmcnt(1)
	v_add_f32_e32 v8, v10, v49
	v_lshl_add_u64 v[4:5], v[86:87], 0, v[4:5]
	s_waitcnt lgkmcnt(0)
	v_add_f32_e32 v49, v11, v50
	v_mul_f32_e32 v50, 0x3fb8aa3b, v8
	v_lshl_add_u64 v[8:9], v[86:87], 0, v[6:7]
	global_load_dwordx4 v[4:7], v[4:5], off
	s_nop 0
	global_load_dwordx4 v[8:11], v[8:9], off
	v_or_b32_e32 v112, s0, v207
	v_ashrrev_i32_e32 v113, 31, v112
	v_lshlrev_b64 v[112:113], 7, v[112:113]
	v_lshl_add_u64 v[112:113], v[86:87], 0, v[112:113]
	v_or_b32_e32 v114, s0, v208
	v_ashrrev_i32_e32 v115, 31, v114
	v_lshlrev_b64 v[114:115], 7, v[114:115]
	v_lshl_add_u64 v[114:115], v[86:87], 0, v[114:115]
	global_load_dwordx4 v[104:107], v[112:113], off
	global_load_dwordx4 v[108:111], v[114:115], off
	global_load_dwordx4 v[116:119], v[174:175], off
	global_load_dwordx4 v[120:123], v[174:175], off offset:64
	global_load_dwordx4 v[124:127], v[174:175], off offset:128
	global_load_dwordx4 v[128:131], v[174:175], off offset:192
	s_addc_u32 s26, s9, s21
	v_div_scale_f32 v53, s[20:21], v88, v88, 1.0
	v_rcp_f32_e32 v85, v53
	v_mul_f32_e32 v49, 0x3fb8aa3b, v49
	v_exp_f32_e32 v50, v50
	v_exp_f32_e32 v49, v49
	v_fma_f32 v89, -v53, v85, 1.0
	v_fmac_f32_e32 v85, v89, v85
	v_div_scale_f32 v89, vcc, 1.0, v88, 1.0
	s_lshl_b32 s27, s33, 7
	v_mul_f32_e32 v92, v89, v85
	v_sub_f32_e32 v49, v50, v49
	s_add_u32 s20, s1, s27
	v_fma_f32 v93, -v53, v92, v89
	v_add_f32_e32 v49, v205, v49
	s_addc_u32 s21, s26, 0
	v_fmac_f32_e32 v92, v93, v85
	v_lshl_add_u64 v[50:51], s[20:21], 0, v[188:189]
	v_fma_f32 v53, -v53, v92, v89
	v_div_scale_f32 v89, s[20:21], v84, v84, v49
	v_rcp_f32_e32 v93, v89
	v_div_fmas_f32 v53, v53, v85, v92
	v_div_fixup_f32 v88, v53, v88, 1.0
	s_add_i32 s31, s31, s88
	v_fma_f32 v53, -v89, v93, 1.0
	v_fmac_f32_e32 v93, v53, v93
	v_div_scale_f32 v53, vcc, v49, v84, v49
	v_mul_f32_e32 v85, v53, v93
	v_fma_f32 v92, -v89, v85, v53
	v_fmac_f32_e32 v85, v92, v93
	v_fma_f32 v53, -v89, v85, v53
	v_div_fmas_f32 v53, v53, v93, v85
	v_div_fixup_f32 v84, v53, v84, v49
	v_pk_mul_f32 v[14:15], v[14:15], v[84:85] op_sel_hi:[1,0]
	v_pk_mul_f32 v[12:13], v[12:13], v[84:85] op_sel_hi:[1,0]
	v_pk_fma_f32 v[82:83], v[88:89], v[82:83], v[14:15] op_sel_hi:[0,1,1] neg_lo:[0,0,1] neg_hi:[0,0,1]
	v_pk_fma_f32 v[80:81], v[88:89], v[80:81], v[12:13] op_sel_hi:[0,1,1] neg_lo:[0,0,1] neg_hi:[0,0,1]
	v_pk_mul_f32 v[12:13], v[82:83], v[82:83]
	v_pk_mul_f32 v[14:15], v[80:81], v[80:81]
	v_pk_mul_f32 v[64:65], v[64:65], v[84:85] op_sel_hi:[1,0]
	v_pk_mov_b32 v[92:93], v[14:15], v[12:13] op_sel:[1,0]
	v_mov_b32_e32 v15, v13
	v_pk_add_f32 v[12:13], v[92:93], v[14:15]
	v_pk_mul_f32 v[14:15], v[66:67], v[84:85] op_sel_hi:[1,0]
	v_pk_fma_f32 v[64:65], v[88:89], v[76:77], v[64:65] op_sel_hi:[0,1,1] neg_lo:[0,0,1] neg_hi:[0,0,1]
	v_pk_fma_f32 v[66:67], v[88:89], v[78:79], v[14:15] op_sel_hi:[0,1,1] neg_lo:[0,0,1] neg_hi:[0,0,1]
	v_pk_mul_f32 v[14:15], v[66:67], v[66:67]
	v_pk_mul_f32 v[76:77], v[64:65], v[64:65]
	v_pk_add_f32 v[12:13], v[12:13], v[12:13] op_sel_hi:[0,1]
	v_pk_mov_b32 v[78:79], v[76:77], v[14:15] op_sel:[1,0]
	v_mov_b32_e32 v77, v15
	v_pk_add_f32 v[14:15], v[78:79], v[76:77]
	v_pk_mul_f32 v[76:77], v[60:61], v[84:85] op_sel_hi:[1,0]
	v_pk_mul_f32 v[60:61], v[62:63], v[84:85] op_sel_hi:[1,0]
	v_pk_fma_f32 v[62:63], v[88:89], v[72:73], v[76:77] op_sel_hi:[0,1,1] neg_lo:[0,0,1] neg_hi:[0,0,1]
	v_pk_mul_f32 v[76:77], v[56:57], v[84:85] op_sel_hi:[1,0]
	v_pk_mul_f32 v[56:57], v[58:59], v[84:85] op_sel_hi:[1,0]
	v_pk_fma_f32 v[58:59], v[88:89], v[68:69], v[76:77] op_sel_hi:[0,1,1] neg_lo:[0,0,1] neg_hi:[0,0,1]
	v_pk_fma_f32 v[60:61], v[88:89], v[74:75], v[60:61] op_sel_hi:[0,1,1] neg_lo:[0,0,1] neg_hi:[0,0,1]
	v_mul_f32_e32 v12, v62, v62
	v_pk_fma_f32 v[72:73], v[62:63], v[62:63], v[12:13] op_sel_hi:[1,1,0]
	v_mul_f32_e32 v12, v60, v60
	v_pk_fma_f32 v[74:75], v[60:61], v[60:61], v[12:13] op_sel_hi:[1,1,0]
	v_mul_f32_e32 v72, v58, v58
	v_mul_f32_e32 v74, v59, v59
	v_pk_fma_f32 v[56:57], v[88:89], v[70:71], v[56:57] op_sel_hi:[0,1,1] neg_lo:[0,0,1] neg_hi:[0,0,1]
	v_pk_add_f32 v[14:15], v[14:15], v[14:15] op_sel_hi:[0,1]
	s_waitcnt vmcnt(7)
	ds_write_b128 v167, v[4:7]
	s_waitcnt vmcnt(6)
	ds_write_b128 v167, v[8:11] offset:1152
	ds_read_b64 v[4:5], v209
	ds_read_b64 v[76:77], v209 offset:32
	ds_read_b64 v[78:79], v209 offset:64
	ds_read_b64 v[84:85], v209 offset:96
	v_mul_f32_e32 v12, v56, v56
	v_mul_f32_e32 v14, v57, v57
	v_pk_add_f32 v[12:13], v[12:13], v[14:15]
	s_waitcnt lgkmcnt(3)
; #define LAS __attribute__((address_space(3)))
; DI unsigned pk2(float lo, float hi) { f32x2_t v = {lo, hi}; bf16x2_t b = __builtin_convertvector(v, bf16x2_t); return __builtin_bit_cast(unsigned, b); }
; DI float silu_f(float x) { return x * __builtin_amdgcn_rcpf(1.f + __expf(-x)); }
; DI void mixerB2_unit(int u, int l, const bf16* PROJ, bf16* YC, const float* dlam_l, const float* dnw_l, const float* kmax_l, LAS char* lds, int tid, int wave, int lane) {
;     ...
;     const float lam_init = 0.8f - 0.6f * __expf(-0.3f * (float)l);
;     const float lam = __expf(pa) - __expf(pb) + lam_init;
;     LAS char* sc = lds + 4 * KV_TILE + wave * (16 * VT_PITCH);
; #pragma unroll
;     for (int qt = 0; qt < 2; ++qt) {
;         const int tok0 = q0w + 16 * qt;
;         const float i1 = 1.f / ol1[qt][0], i2 = lam / ol2[qt][0];
;         f32x4 o[4]; float ss = 0.f;
; #pragma unroll
;         for (int c = 0; c < 4; ++c) { o[c] = o1[qt][c] * i1 - o2[qt][c] * i2; ss += (o[c][0] * o[c][0] + o[c][1] * o[c][1]) + (o[c][2] * o[c][2] + o[c][3] * o[c][3]); }
;         ss += __shfl_xor(ss, 16); ss += __shfl_xor(ss, 32);
;         const float rstd = rsqrtf(ss * (1.f / 64.f) + EPS) * (1.f - lam_init);
;         rows16_load(sc, gbase, 64, tok0, 1, lane);
;         u32x2 gv[4];
; #pragma unroll
;         for (int c = 0; c < 4; ++c) gv[c] = *(const LAS u32x2*)(sc + r * VT_PITCH + (16 * c + 4 * g) * 2);
; #pragma unroll
;         for (int c = 0; c < 4; ++c) { const int dd = 16 * c + 4 * g;
;             const f32x4 nw = *(const f32x4*)(dnw_l + dd);
;             const f32x4 y = o[c] * rstd * nw;
;             u32x2 w; w.x = pk2(y[0] * silu_f(bflo(gv[c].x)), y[1] * silu_f(bfhi(gv[c].x))); w.y = pk2(y[2] * silu_f(bflo(gv[c].y)), y[3] * silu_f(bfhi(gv[c].y)));
	v_and_b32_e32 v7, 0xffff0000, v4
	v_mul_f32_e32 v8, 0xbfb8aa3b, v7
	v_exp_f32_e32 v10, v8
	v_and_b32_e32 v11, 0xffff0000, v5
	v_pk_add_f32 v[8:9], v[72:73], v[74:75]
	s_waitcnt lgkmcnt(2)
	v_lshlrev_b32_e32 v72, 16, v77
	v_add_f32_e32 v53, 1.0, v10
	v_lshlrev_b32_e32 v10, 16, v5
	v_mul_f32_e32 v5, 0xbfb8aa3b, v10
	v_exp_f32_e32 v68, v5
	v_mul_f32_e32 v5, 0xbfb8aa3b, v11
	v_exp_f32_e32 v69, v5
	v_rcp_f32_e32 v5, v53
	v_add_f32_e32 v53, 1.0, v68
	v_rcp_f32_e32 v70, v53
	v_add_f32_e32 v53, 1.0, v69
	v_rcp_f32_e32 v71, v53
	v_and_b32_e32 v73, 0xffff0000, v77
	v_mul_f32_e32 v53, 0xbfb8aa3b, v72
	v_lshlrev_b32_e32 v6, 16, v4
	v_exp_f32_e32 v53, v53
	v_mul_f32_e32 v74, 0xbfb8aa3b, v73
	v_mul_f32_e32 v4, 0xbfb8aa3b, v6
	v_exp_f32_e32 v75, v74
	v_exp_f32_e32 v4, v4
	v_pk_add_f32 v[88:89], v[8:9], v[12:13]
	v_lshlrev_b32_e32 v12, 16, v76
	v_and_b32_e32 v13, 0xffff0000, v76
	v_add_f32_e32 v53, 1.0, v53
	s_waitcnt lgkmcnt(1)
	v_lshlrev_b32_e32 v76, 16, v78
	v_rcp_f32_e32 v74, v53
	v_add_f32_e32 v53, 1.0, v75
	v_and_b32_e32 v77, 0xffff0000, v78
	v_mul_f32_e32 v75, 0xbfb8aa3b, v76
	v_add_f32_e32 v4, 1.0, v4
	v_exp_f32_e32 v78, v75
	v_mul_f32_e32 v75, 0xbfb8aa3b, v77
	v_rcp_f32_e32 v4, v4
	v_exp_f32_e32 v92, v75
	v_rcp_f32_e32 v75, v53
	v_add_f32_e32 v53, 1.0, v78
	v_pk_mul_f32 v[68:69], v[4:5], v[6:7]
	v_mul_f32_e32 v4, 0xbfb8aa3b, v12
	v_rcp_f32_e32 v78, v53
	v_add_f32_e32 v53, 1.0, v92
	v_lshlrev_b32_e32 v92, 16, v79
	v_exp_f32_e32 v14, v4
	v_mul_f32_e32 v4, 0xbfb8aa3b, v13
	v_and_b32_e32 v93, 0xffff0000, v79
	v_mul_f32_e32 v79, 0xbfb8aa3b, v92
	v_pk_mul_f32 v[70:71], v[70:71], v[10:11]
	v_exp_f32_e32 v15, v4
	v_exp_f32_e32 v94, v79
	v_mul_f32_e32 v79, 0xbfb8aa3b, v93
	v_exp_f32_e32 v95, v79
	v_rcp_f32_e32 v79, v53
	v_add_f32_e32 v53, 1.0, v94
	v_rcp_f32_e32 v94, v53
	v_add_f32_e32 v53, 1.0, v95
	v_add_f32_e32 v14, 1.0, v14
	v_add_f32_e32 v15, 1.0, v15
	v_rcp_f32_e32 v95, v53
	v_rcp_f32_e32 v14, v14
	v_rcp_f32_e32 v15, v15
	v_pk_mul_f32 v[98:99], v[74:75], v[72:73]
	v_pk_mul_f32 v[100:101], v[78:79], v[76:77]
	v_pk_mul_f32 v[92:93], v[94:95], v[92:93]
	s_waitcnt lgkmcnt(0)
	v_lshlrev_b32_e32 v94, 16, v84
	v_pk_mul_f32 v[96:97], v[14:15], v[12:13]
	v_and_b32_e32 v95, 0xffff0000, v84
	v_mul_f32_e32 v12, 0xbfb8aa3b, v94
	v_exp_f32_e32 v12, v12
	v_mul_f32_e32 v13, 0xbfb8aa3b, v95
	v_exp_f32_e32 v13, v13
	v_lshlrev_b32_e32 v84, 16, v85
	v_add_f32_e32 v12, 1.0, v12
	v_rcp_f32_e32 v102, v12
	v_add_f32_e32 v12, 1.0, v13
	v_div_scale_f32 v13, s[20:21], v52, v52, 1.0
	v_rcp_f32_e32 v14, v13
	v_rcp_f32_e32 v103, v12
	v_and_b32_e32 v85, 0xffff0000, v85
	s_add_i32 s30, s30, s56
	v_fma_f32 v12, -v13, v14, 1.0
	v_fmac_f32_e32 v14, v12, v14
	v_div_scale_f32 v12, vcc, 1.0, v52, 1.0
	v_mul_f32_e32 v15, v12, v14
	v_fma_f32 v53, -v13, v15, v12
	v_fmac_f32_e32 v15, v53, v14
	v_fma_f32 v12, -v13, v15, v12
	v_div_scale_f32 v13, s[20:21], v48, v48, v49
	v_rcp_f32_e32 v53, v13
	v_div_fmas_f32 v12, v12, v14, v15
	v_div_fixup_f32 v14, v12, v52, 1.0
	s_mov_b32 s20, 0x3c800000
	v_fma_f32 v12, -v13, v53, 1.0
	v_fmac_f32_e32 v53, v12, v53
	v_div_scale_f32 v12, vcc, v49, v48, v49
	v_mul_f32_e32 v15, v12, v53
	v_fma_f32 v52, -v13, v15, v12
	v_fmac_f32_e32 v15, v52, v53
	v_fma_f32 v12, -v13, v15, v12
	v_div_fmas_f32 v12, v12, v53, v15
	v_div_fixup_f32 v12, v12, v48, v49
	v_pk_mul_f32 v[34:35], v[34:35], v[12:13] op_sel_hi:[1,0]
	v_pk_mul_f32 v[32:33], v[32:33], v[12:13] op_sel_hi:[1,0]
	v_pk_fma_f32 v[34:35], v[14:15], v[46:47], v[34:35] op_sel_hi:[0,1,1] neg_lo:[0,0,1] neg_hi:[0,0,1]
	v_pk_fma_f32 v[32:33], v[14:15], v[44:45], v[32:33] op_sel_hi:[0,1,1] neg_lo:[0,0,1] neg_hi:[0,0,1]
	v_pk_mul_f32 v[26:27], v[26:27], v[12:13] op_sel_hi:[1,0]
	v_pk_mul_f32 v[24:25], v[24:25], v[12:13] op_sel_hi:[1,0]
	v_pk_mul_f32 v[44:45], v[34:35], v[34:35]
	v_pk_mul_f32 v[46:47], v[32:33], v[32:33]
	v_pk_fma_f32 v[24:25], v[14:15], v[40:41], v[24:25] op_sel_hi:[0,1,1] neg_lo:[0,0,1] neg_hi:[0,0,1]
	v_pk_fma_f32 v[26:27], v[14:15], v[42:43], v[26:27] op_sel_hi:[0,1,1] neg_lo:[0,0,1] neg_hi:[0,0,1]
	v_pk_mov_b32 v[48:49], v[46:47], v[44:45] op_sel:[1,0]
	v_mov_b32_e32 v47, v45
	v_pk_mul_f32 v[40:41], v[26:27], v[26:27]
	v_pk_mul_f32 v[42:43], v[24:25], v[24:25]
	v_pk_add_f32 v[44:45], v[48:49], v[46:47]
	v_pk_mov_b32 v[46:47], v[42:43], v[40:41] op_sel:[1,0]
	v_mov_b32_e32 v43, v41
	v_pk_add_f32 v[40:41], v[46:47], v[42:43]
	v_pk_mul_f32 v[42:43], v[20:21], v[12:13] op_sel_hi:[1,0]
	v_pk_mul_f32 v[20:21], v[22:23], v[12:13] op_sel_hi:[1,0]
	v_pk_fma_f32 v[22:23], v[14:15], v[36:37], v[42:43] op_sel_hi:[0,1,1] neg_lo:[0,0,1] neg_hi:[0,0,1]
	v_mul_f32_e32 v36, v22, v22
	v_pk_fma_f32 v[20:21], v[14:15], v[38:39], v[20:21] op_sel_hi:[0,1,1] neg_lo:[0,0,1] neg_hi:[0,0,1]
	v_pk_fma_f32 v[36:37], v[22:23], v[22:23], v[36:37] op_sel_hi:[1,1,0]
	v_pk_mul_f32 v[16:17], v[16:17], v[12:13] op_sel_hi:[1,0]
	v_mul_f32_e32 v36, v20, v20
	v_pk_mul_f32 v[12:13], v[18:19], v[12:13] op_sel_hi:[1,0]
	v_pk_add_f32 v[44:45], v[44:45], v[44:45] op_sel_hi:[0,1]
	v_pk_add_f32 v[40:41], v[40:41], v[40:41] op_sel_hi:[0,1]
	v_pk_fma_f32 v[38:39], v[20:21], v[20:21], v[36:37] op_sel_hi:[1,1,0]
	v_pk_fma_f32 v[12:13], v[14:15], v[30:31], v[12:13] op_sel_hi:[0,1,1] neg_lo:[0,0,1] neg_hi:[0,0,1]
	v_pk_fma_f32 v[14:15], v[14:15], v[28:29], v[16:17] op_sel_hi:[0,1,1] neg_lo:[0,0,1] neg_hi:[0,0,1]
	v_mul_f32_e32 v36, v14, v14
	v_mul_f32_e32 v38, v15, v15
	v_mul_f32_e32 v44, v12, v12
	v_mul_f32_e32 v40, v13, v13
	v_pk_add_f32 v[16:17], v[36:37], v[38:39]
	v_pk_add_f32 v[18:19], v[44:45], v[40:41]
	v_mul_f32_e32 v28, 0xbfb8aa3b, v84
	v_pk_add_f32 v[16:17], v[16:17], v[18:19]
	v_mov_b32_e32 v19, v88
	v_mov_b32_e32 v18, v16
	v_mov_b32_e32 v88, v17
	v_pk_add_f32 v[16:17], v[18:19], v[88:89]
	ds_bpermute_b32 v19, v184, v17
	ds_bpermute_b32 v18, v184, v16
	v_mul_f32_e32 v29, 0xbfb8aa3b, v85
	v_exp_f32_e32 v28, v28
	v_exp_f32_e32 v29, v29
	s_cmpk_gt_i32 s31, 0xff
	s_waitcnt lgkmcnt(0)
; #define LAS __attribute__((address_space(3)))
; DI unsigned pk2(float lo, float hi) { f32x2_t v = {lo, hi}; bf16x2_t b = __builtin_convertvector(v, bf16x2_t); return __builtin_bit_cast(unsigned, b); }
; DI float silu_f(float x) { return x * __builtin_amdgcn_rcpf(1.f + __expf(-x)); }
; DI void mixerB2_unit(int u, int l, const bf16* PROJ, bf16* YC, const float* dlam_l, const float* dnw_l, const float* kmax_l, LAS char* lds, int tid, int wave, int lane) {
;     ...
;         const float rstd = rsqrtf(ss * (1.f / 64.f) + EPS) * (1.f - lam_init);
;         rows16_load(sc, gbase, 64, tok0, 1, lane);
;         u32x2 gv[4];
; #pragma unroll
;         for (int c = 0; c < 4; ++c) gv[c] = *(const LAS u32x2*)(sc + r * VT_PITCH + (16 * c + 4 * g) * 2);
; #pragma unroll
;         for (int c = 0; c < 4; ++c) { const int dd = 16 * c + 4 * g;
;             const f32x4 nw = *(const f32x4*)(dnw_l + dd);
;             const f32x4 y = o[c] * rstd * nw;
;             u32x2 w; w.x = pk2(y[0] * silu_f(bflo(gv[c].x)), y[1] * silu_f(bfhi(gv[c].x))); w.y = pk2(y[2] * silu_f(bflo(gv[c].y)), y[3] * silu_f(bfhi(gv[c].y)));
;             *(LAS u32x2*)(sc + r * VT_PITCH + dd * 2) = w; }
;         rows16_store(sc, YC + (size_t)b * T * 1024 + 256 + h * 64, 1024, tok0, 1, lane);
	v_pk_add_f32 v[16:17], v[16:17], v[18:19]
	ds_bpermute_b32 v19, v185, v17
	ds_bpermute_b32 v18, v185, v16
	v_add_f32_e32 v28, 1.0, v28
	v_add_f32_e32 v29, 1.0, v29
	v_rcp_f32_e32 v28, v28
	v_rcp_f32_e32 v29, v29
	s_waitcnt lgkmcnt(0)
	v_pk_add_f32 v[16:17], v[16:17], v[18:19]
	v_pk_mul_f32 v[18:19], v[28:29], v[84:85]
	v_pk_fma_f32 v[44:45], v[16:17], s[20:21], v[190:191] op_sel_hi:[1,0,0]
	v_lshlrev_b64 v[28:29], 11, v[90:91]
	v_mul_f32_e32 v16, 0x4b800000, v45
	v_cmp_gt_f32_e32 vcc, s15, v45
	s_nop 1
	v_cndmask_b32_e32 v16, v45, v16, vcc
	v_rsq_f32_e32 v30, v16
	v_pk_mul_f32 v[16:17], v[102:103], v[94:95]
	v_mul_f32_e32 v45, 0x4b800000, v44
	v_mul_f32_e32 v31, 0x45800000, v30
	v_cndmask_b32_e32 v30, v30, v31, vcc
	v_mul_f32_e32 v30, v206, v30
	v_pk_mul_f32 v[36:37], v[80:81], v[30:31] op_sel_hi:[1,0]
	v_pk_mul_f32 v[38:39], v[82:83], v[30:31] op_sel_hi:[1,0]
	s_waitcnt vmcnt(3)
	v_pk_mul_f32 v[8:9], v[116:117], v[36:37]
	v_pk_mul_f32 v[10:11], v[118:119], v[38:39]
	v_pk_mul_f32 v[8:9], v[68:69], v[8:9]
	v_pk_mul_f32 v[10:11], v[70:71], v[10:11]
	v_cvt_pk_bf16_f32 v8, v8, v9
	v_cvt_pk_bf16_f32 v9, v10, v11
	ds_write_b64 v209, v[8:9]
	v_pk_mul_f32 v[8:9], v[64:65], v[30:31] op_sel_hi:[1,0]
	v_pk_mul_f32 v[10:11], v[66:67], v[30:31] op_sel_hi:[1,0]
	s_waitcnt vmcnt(2)
	v_pk_mul_f32 v[4:5], v[120:121], v[8:9]
	v_pk_mul_f32 v[6:7], v[122:123], v[10:11]
	v_pk_mul_f32 v[4:5], v[96:97], v[4:5]
	v_pk_mul_f32 v[6:7], v[98:99], v[6:7]
	v_cvt_pk_bf16_f32 v4, v4, v5
	v_cvt_pk_bf16_f32 v5, v6, v7
	ds_write_b64 v210, v[4:5]
	v_pk_mul_f32 v[4:5], v[62:63], v[30:31] op_sel_hi:[1,0]
	v_pk_mul_f32 v[6:7], v[60:61], v[30:31] op_sel_hi:[1,0]
	s_waitcnt vmcnt(1)
	v_pk_mul_f32 v[4:5], v[124:125], v[4:5]
	v_pk_mul_f32 v[6:7], v[126:127], v[6:7]
	v_pk_mul_f32 v[4:5], v[100:101], v[4:5]
	v_pk_mul_f32 v[6:7], v[92:93], v[6:7]
	v_cvt_pk_bf16_f32 v4, v4, v5
	v_cvt_pk_bf16_f32 v5, v6, v7
	ds_write_b64 v211, v[4:5]
	v_pk_mul_f32 v[4:5], v[58:59], v[30:31] op_sel_hi:[1,0]
	v_pk_mul_f32 v[6:7], v[56:57], v[30:31] op_sel_hi:[1,0]
	s_waitcnt vmcnt(0)
	v_pk_mul_f32 v[4:5], v[128:129], v[4:5]
	v_pk_mul_f32 v[6:7], v[130:131], v[6:7]
	v_pk_mul_f32 v[4:5], v[16:17], v[4:5]
	v_pk_mul_f32 v[6:7], v[18:19], v[6:7]
	v_cvt_pk_bf16_f32 v4, v4, v5
	v_cvt_pk_bf16_f32 v5, v6, v7
	ds_write_b64 v212, v[4:5]
	ds_read_b128 v[4:7], v167
	ds_read_b128 v[8:11], v167 offset:1152
	v_lshl_add_u64 v[16:17], v[50:51], 0, v[28:29]
	v_lshlrev_b64 v[18:19], 11, v[54:55]
	v_lshl_add_u64 v[18:19], v[50:51], 0, v[18:19]
	s_waitcnt lgkmcnt(1)
	global_store_dwordx4 v[16:17], v[4:7], off offset:512
	s_waitcnt lgkmcnt(0)
	global_store_dwordx4 v[18:19], v[8:11], off offset:512
	v_or_b32_e32 v4, s0, v207
	v_ashrrev_i32_e32 v5, 31, v4
	v_lshlrev_b64 v[6:7], 7, v[4:5]
	v_lshl_add_u64 v[8:9], v[86:87], 0, v[6:7]
	v_or_b32_e32 v6, s0, v208
	v_ashrrev_i32_e32 v7, 31, v6
	v_lshlrev_b64 v[10:11], 7, v[6:7]
	v_lshl_add_u64 v[16:17], v[86:87], 0, v[10:11]
	v_cmp_gt_f32_e32 vcc, s15, v44
	ds_write_b128 v167, v[104:107]
	ds_write_b128 v167, v[108:111] offset:1152
	v_cndmask_b32_e32 v44, v44, v45, vcc
	v_rsq_f32_e32 v44, v44
	v_lshlrev_b64 v[4:5], 11, v[4:5]
	v_lshl_add_u64 v[4:5], v[50:51], 0, v[4:5]
	v_mul_f32_e32 v45, 0x45800000, v44
	v_cndmask_b32_e32 v46, v44, v45, vcc
	ds_read_b64 v[8:9], v209
	ds_read_b64 v[16:17], v209 offset:32
	ds_read_b64 v[18:19], v209 offset:64
	ds_read_b64 v[44:45], v209 offset:96
	v_mul_f32_e32 v46, v206, v46
	v_pk_mul_f32 v[10:11], v[32:33], v[46:47] op_sel_hi:[1,0]
	v_pk_mul_f32 v[32:33], v[34:35], v[46:47] op_sel_hi:[1,0]
	s_waitcnt vmcnt(2)
	v_pk_mul_f32 v[28:29], v[116:117], v[10:11]
	v_pk_mul_f32 v[30:31], v[118:119], v[32:33]
	s_waitcnt lgkmcnt(3)
; #define LAS __attribute__((address_space(3)))
; DI unsigned pk2(float lo, float hi) { f32x2_t v = {lo, hi}; bf16x2_t b = __builtin_convertvector(v, bf16x2_t); return __builtin_bit_cast(unsigned, b); }
; DI float silu_f(float x) { return x * __builtin_amdgcn_rcpf(1.f + __expf(-x)); }
; DI void mixerB2_unit(int u, int l, const bf16* PROJ, bf16* YC, const float* dlam_l, const float* dnw_l, const float* kmax_l, LAS char* lds, int tid, int wave, int lane) {
;     ...
;         for (int c = 0; c < 4; ++c) gv[c] = *(const LAS u32x2*)(sc + r * VT_PITCH + (16 * c + 4 * g) * 2);
; #pragma unroll
;         for (int c = 0; c < 4; ++c) { const int dd = 16 * c + 4 * g;
;             const f32x4 nw = *(const f32x4*)(dnw_l + dd);
;             const f32x4 y = o[c] * rstd * nw;
;             u32x2 w; w.x = pk2(y[0] * silu_f(bflo(gv[c].x)), y[1] * silu_f(bfhi(gv[c].x))); w.y = pk2(y[2] * silu_f(bflo(gv[c].y)), y[3] * silu_f(bfhi(gv[c].y)));
;             *(LAS u32x2*)(sc + r * VT_PITCH + dd * 2) = w; }
;         rows16_store(sc, YC + (size_t)b * T * 1024 + 256 + h * 64, 1024, tok0, 1, lane);
	v_lshlrev_b32_e32 v32, 16, v8
	v_and_b32_e32 v33, 0xffff0000, v8
	v_mul_f32_e32 v8, 0xbfb8aa3b, v32
	v_exp_f32_e32 v8, v8
	v_mul_f32_e32 v34, 0xbfb8aa3b, v33
	v_exp_f32_e32 v35, v34
	v_lshlrev_b32_e32 v48, 16, v9
	v_add_f32_e32 v8, 1.0, v8
	v_rcp_f32_e32 v34, v8
	v_and_b32_e32 v49, 0xffff0000, v9
	v_mul_f32_e32 v47, 0xbfb8aa3b, v48
	v_exp_f32_e32 v47, v47
	v_mul_f32_e32 v52, 0xbfb8aa3b, v49
	v_exp_f32_e32 v53, v52
	v_add_f32_e32 v35, 1.0, v35
	v_add_f32_e32 v47, 1.0, v47
	v_rcp_f32_e32 v35, v35
	v_rcp_f32_e32 v52, v47
	v_add_f32_e32 v47, 1.0, v53
	v_rcp_f32_e32 v53, v47
	v_pk_mul_f32 v[32:33], v[34:35], v[32:33]
	v_pk_mul_f32 v[24:25], v[24:25], v[46:47] op_sel_hi:[1,0]
	v_pk_mul_f32 v[28:29], v[32:33], v[28:29]
	v_pk_mul_f32 v[32:33], v[52:53], v[48:49]
	v_cvt_pk_bf16_f32 v28, v28, v29
	v_pk_mul_f32 v[30:31], v[32:33], v[30:31]
	v_pk_mul_f32 v[26:27], v[26:27], v[46:47] op_sel_hi:[1,0]
	v_cvt_pk_bf16_f32 v29, v30, v31
	ds_write_b64 v209, v[28:29]
	s_waitcnt lgkmcnt(3)
	v_and_b32_e32 v29, 0xffff0000, v16
	v_mul_f32_e32 v30, 0xbfb8aa3b, v29
	v_exp_f32_e32 v30, v30
	v_lshlrev_b32_e32 v28, 16, v16
	v_mul_f32_e32 v16, 0xbfb8aa3b, v28
	v_and_b32_e32 v31, 0xffff0000, v17
	v_add_f32_e32 v32, 1.0, v30
	v_lshlrev_b32_e32 v30, 16, v17
	v_mul_f32_e32 v17, 0xbfb8aa3b, v30
	v_exp_f32_e32 v16, v16
	v_exp_f32_e32 v33, v17
	v_mul_f32_e32 v17, 0xbfb8aa3b, v31
	v_exp_f32_e32 v34, v17
	v_add_f32_e32 v16, 1.0, v16
	v_rcp_f32_e32 v16, v16
	v_rcp_f32_e32 v17, v32
	v_add_f32_e32 v32, 1.0, v33
	v_add_f32_e32 v33, 1.0, v34
	v_rcp_f32_e32 v32, v32
	v_rcp_f32_e32 v33, v33
	s_waitcnt vmcnt(2)
	v_pk_mul_f32 v[24:25], v[120:121], v[24:25]
	v_pk_mul_f32 v[16:17], v[16:17], v[28:29]
	v_pk_mul_f32 v[26:27], v[122:123], v[26:27]
	v_pk_mul_f32 v[16:17], v[16:17], v[24:25]
	v_pk_mul_f32 v[24:25], v[32:33], v[30:31]
	v_cvt_pk_bf16_f32 v16, v16, v17
	v_pk_mul_f32 v[24:25], v[24:25], v[26:27]
	v_pk_mul_f32 v[20:21], v[20:21], v[46:47] op_sel_hi:[1,0]
	v_cvt_pk_bf16_f32 v17, v24, v25
	ds_write_b64 v210, v[16:17]
	v_pk_mul_f32 v[16:17], v[22:23], v[46:47] op_sel_hi:[1,0]
	s_waitcnt lgkmcnt(3)
	v_and_b32_e32 v23, 0xffff0000, v18
	v_mul_f32_e32 v24, 0xbfb8aa3b, v23
	v_exp_f32_e32 v24, v24
	v_lshlrev_b32_e32 v22, 16, v18
	v_mul_f32_e32 v18, 0xbfb8aa3b, v22
	v_and_b32_e32 v25, 0xffff0000, v19
	v_add_f32_e32 v26, 1.0, v24
	v_lshlrev_b32_e32 v24, 16, v19
	v_mul_f32_e32 v19, 0xbfb8aa3b, v24
	v_exp_f32_e32 v18, v18
	v_exp_f32_e32 v27, v19
	v_mul_f32_e32 v19, 0xbfb8aa3b, v25
	v_exp_f32_e32 v28, v19
	v_add_f32_e32 v18, 1.0, v18
	v_rcp_f32_e32 v18, v18
	v_rcp_f32_e32 v19, v26
	v_add_f32_e32 v26, 1.0, v27
	v_add_f32_e32 v27, 1.0, v28
	v_rcp_f32_e32 v26, v26
	v_rcp_f32_e32 v27, v27
	s_waitcnt vmcnt(1)
	v_pk_mul_f32 v[16:17], v[124:125], v[16:17]
	v_pk_mul_f32 v[18:19], v[18:19], v[22:23]
	v_pk_mul_f32 v[20:21], v[126:127], v[20:21]
	v_pk_mul_f32 v[16:17], v[16:17], v[18:19]
	v_pk_mul_f32 v[18:19], v[26:27], v[24:25]
	v_pk_mul_f32 v[12:13], v[12:13], v[46:47] op_sel_hi:[1,0]
	v_pk_mul_f32 v[18:19], v[20:21], v[18:19]
	v_cvt_pk_bf16_f32 v16, v16, v17
	v_cvt_pk_bf16_f32 v17, v18, v19
	s_waitcnt vmcnt(0)
	v_pk_mul_f32 v[10:11], v[12:13], v[130:131]
	s_waitcnt lgkmcnt(2)
	v_lshlrev_b32_e32 v12, 16, v44
	v_and_b32_e32 v13, 0xffff0000, v44
	ds_write_b64 v211, v[16:17]
	v_mul_f32_e32 v16, 0xbfb8aa3b, v12
	v_mul_f32_e32 v17, 0xbfb8aa3b, v13
	v_exp_f32_e32 v16, v16
	v_exp_f32_e32 v17, v17
	v_pk_mul_f32 v[14:15], v[14:15], v[46:47] op_sel_hi:[1,0]
	s_nop 0
	v_pk_mul_f32 v[8:9], v[14:15], v[128:129]
	v_add_f32_e32 v14, 1.0, v16
	v_add_f32_e32 v15, 1.0, v17
	v_lshlrev_b32_e32 v16, 16, v45
	v_and_b32_e32 v17, 0xffff0000, v45
	v_mul_f32_e32 v18, 0xbfb8aa3b, v16
	v_mul_f32_e32 v19, 0xbfb8aa3b, v17
	v_exp_f32_e32 v18, v18
	v_exp_f32_e32 v19, v19
	v_rcp_f32_e32 v14, v14
	v_rcp_f32_e32 v15, v15
	v_add_f32_e32 v18, 1.0, v18
	v_add_f32_e32 v19, 1.0, v19
	v_rcp_f32_e32 v18, v18
	v_rcp_f32_e32 v19, v19
	v_pk_mul_f32 v[12:13], v[14:15], v[12:13]
	s_nop 0
	v_pk_mul_f32 v[8:9], v[12:13], v[8:9]
	v_pk_mul_f32 v[12:13], v[18:19], v[16:17]
	v_cvt_pk_bf16_f32 v8, v8, v9
	v_pk_mul_f32 v[10:11], v[12:13], v[10:11]
	s_nop 0
	v_cvt_pk_bf16_f32 v9, v10, v11
	ds_write_b64 v212, v[8:9]
	ds_read_b128 v[8:11], v167
	ds_read_b128 v[12:15], v167 offset:1152
	s_waitcnt lgkmcnt(1)
	global_store_dwordx4 v[4:5], v[8:11], off offset:512
	v_lshlrev_b64 v[4:5], 11, v[6:7]
	v_lshl_add_u64 v[4:5], v[50:51], 0, v[4:5]
	s_waitcnt lgkmcnt(0)
	global_store_dwordx4 v[4:5], v[12:15], off offset:512
	s_cbranch_scc1 .LBB0_262
